# P0: waves 4-7 of each workgroup run the RMSNorm rows before the weight transposes (other waves keep transposes first) so the bandwidth-bound and latency-bound parts overlap
# speedup vs baseline: 1.0132x; 1.0132x over previous
; #define LAS __attribute__((address_space(3)))
; __global__ void __launch_bounds__(512, 2) mk_fwd(Args a) {
;     ...
;     for (int rep0 = 0; rep0 < REP_P0; ++rep0) {
;         LAS float* scr = (LAS float*)(lds + wave * 16384);
;         constexpr int I_IN = (DM / 64) * (NIN / 32), I_A = (512 / 64) * (DM / 32), I_B = (256 / 64) * (DM / 32), I_O = (DM / 64) * (DM / 32), I_U = (DM / 64) * (DFF / 32), I_D = (DFF / 64) * (DM / 32);
;         constexpr int NIT = I_IN + I_A + I_B + I_O + I_U + I_D;
;         for (int it = gw; it < NIT; it += NGW) {
;             int r = it;
;             if (r < I_IN) { p0_transpose_item_fp8(w_in, DM, NIN, (unsigned char*)Win_t, scr, r, lane, 32.f); continue; } r -= I_IN;
.LBB0_14:
	s_or_b64 exec, exec, s[4:5]
	s_lshr_b32 s0, s25, 6
	s_lshl_b32 s1, s2, 3
	s_add_i32 s6, s0, s1
	s_lshl_b32 s25, s24, 3
	s_add_u32 s54, s22, 0x100000
	s_addc_u32 s55, s23, 0
	s_add_u32 s4, s22, 0xb00000
	s_addc_u32 s5, s23, 0
	s_add_u32 s34, s22, 0xd00000
	s_addc_u32 s35, s23, 0
	s_add_u32 s30, s22, 0xf00000
	s_addc_u32 s31, s23, 0
	s_add_u32 s26, s22, 0x1700000
	v_writelane_b32 v255, s4, 2
	s_addc_u32 s27, s23, 0
	v_writelane_b32 v255, s5, 3
	s_mov_b32 s66, 0
	s_cmp_lt_u32 s0, 4
	s_cbranch_scc1 .Lmy_p0_T
	s_mov_b32 s66, 1
	s_mov_b32 s67, s0
	s_mov_b32 s68, s6
	s_mov_b64 s[70:71], s[8:9]
	s_mov_b64 s[72:73], s[12:13]
	s_mov_b64 s[74:75], s[14:15]
	s_mov_b64 s[78:79], s[16:17]
	s_mov_b64 s[80:81], s[42:43]
	s_branch .Lmy_p0_R
.Lmy_p0_T:
	s_cmpk_gt_i32 s6, 0x1d7f
	s_cbranch_scc1 .LBB0_55
	v_and_b32_e32 v0, 63, v254
	v_lshrrev_b32_e32 v40, 3, v0
	v_lshlrev_b32_e32 v0, 4, v254
	v_and_b32_e32 v12, 0x70, v0
	v_lshlrev_b32_e32 v0, 3, v254
	s_lshl_b32 s0, s0, 14
	v_mov_b32_e32 v13, 0
	v_and_b32_e32 v0, 56, v0
	s_add_i32 s0, s0, 0
	v_mul_u32_u24_e32 v6, 0x84, v0
	v_mov_b32_e32 v1, v13
	v_lshlrev_b32_e32 v2, 1, v0
	v_mov_b32_e32 v3, v13
	v_lshlrev_b32_e32 v7, 2, v40
	v_add_u32_e32 v4, s0, v12
	v_lshl_add_u64 v[16:17], s[26:27], 0, v[2:3]
	v_add3_u32 v48, s0, v6, v7
	v_lshl_add_u64 v[20:21], s[30:31], 0, v[2:3]
	v_lshl_add_u64 v[2:3], s[22:23], 0, v[0:1]
	s_mov_b64 s[0:1], 0xb00200
	v_mul_u32_u24_e32 v5, 0x84, v40
	v_lshl_add_u64 v[28:29], v[2:3], 0, s[0:1]
	v_readlane_b32 s0, v255, 2
	s_cmp_lg_u64 s[12:13], 0
	v_readlane_b32 s1, v255, 3
	v_add_u32_e32 v49, v4, v5
	s_mov_b32 s29, 0
	v_lshl_add_u64 v[14:15], s[16:17], 0, v[12:13]
	v_or_b32_e32 v41, 8, v40
	v_or_b32_e32 v42, 16, v40
	v_or_b32_e32 v43, 24, v40
	v_or_b32_e32 v44, 32, v40
	v_or_b32_e32 v45, 40, v40
	v_or_b32_e32 v46, 48, v40
	v_or_b32_e32 v47, 56, v40
	v_lshl_add_u64 v[18:19], s[14:15], 0, v[12:13]
	s_cselect_b64 s[14:15], -1, 0
	v_lshl_add_u64 v[22:23], s[8:9], 0, v[12:13]
	v_lshl_add_u64 v[24:25], s[34:35], 0, v[0:1]
	v_lshl_add_u64 v[26:27], s[50:51], 0, v[12:13]
	v_lshl_add_u64 v[30:31], s[48:49], 0, v[12:13]
	v_lshl_add_u64 v[32:33], s[0:1], 0, v[0:1]
	v_lshl_add_u64 v[34:35], s[44:45], 0, v[12:13]
	v_lshl_add_u64 v[36:37], s[54:55], 0, v[0:1]
	s_lshl_b32 s7, s6, 5
	s_lshl_b32 s9, s25, 5
	s_lshl_b32 s17, s6, 1
	s_lshl_b32 s33, s25, 1
	v_add_u32_e32 v50, 0x420, v49
	v_add_u32_e32 v51, 0x428, v49
	v_add_u32_e32 v52, 0x840, v49
	v_add_u32_e32 v53, 0x848, v49
	v_add_u32_e32 v54, 0xc60, v49
	v_add_u32_e32 v55, 0xc68, v49
	v_add_u32_e32 v56, 0x1080, v49
	v_add_u32_e32 v57, 0x1088, v49
	v_add_u32_e32 v58, 0x14a0, v49
	v_add_u32_e32 v59, 0x14a8, v49
	v_add_u32_e32 v60, 0x18c0, v49
	v_add_u32_e32 v61, 0x18c8, v49
	v_add_u32_e32 v62, 0x1ce0, v49
	v_add_u32_e32 v63, 0x1ce8, v49
	s_mov_b32 s8, 0x42000000
	s_mov_b32 s16, 0x41800000
	s_movk_i32 s48, 0x5000
	s_mov_b32 s49, s6
	s_branch .LBB0_17

; __global__ void __launch_bounds__(512, 2) mk_fwd(Args a) {
;     ...
;         for (int it = gw; it < NIT; it += NGW) {
;             int r = it;
;             if (r < I_IN) { p0_transpose_item_fp8(w_in, DM, NIN, (unsigned char*)Win_t, scr, r, lane, 32.f); continue; } r -= I_IN;
;             if (r < I_A) { p0_transpose_item_fp8(w_a, 512, DM, (unsigned char*)Wa_t, scr, r, lane, 16.f, 768, 0); continue; }     r -= I_A;
;             if (r < I_B) { p0_transpose_item_fp8(w_b, 256, DM, (unsigned char*)Wa_t, scr, r, lane, 16.f, 768, 512); continue; }     r -= I_B;
;             if (r < I_O) { p0_transpose_item_fp8(w_out, DM, DM, (unsigned char*)Wout_t, scr, r, lane, 32.f); continue; } r -= I_O;
;             if (r < I_U) { p0_transpose_item(w_up, DM, DFF, Wup_t, g_mlp, scr, r, lane); continue; } r -= I_U;
;             p0_transpose_item(w_dn, DFF, DM, Wdn_t, nullptr, scr, r, lane);
;         }
;         f32x4 gv[4];
; #pragma unroll
;         for (int j = 0; j < 4; ++j) gv[j] = ((const f32x4*)g_mix)[lane + 64 * j];
;         for (int m = gw; m < TT; m += 2 * NGW) {
.LBB0_55:
	s_cmp_eq_u32 s66, 2
	s_cbranch_scc1 .Lmy_p0_fix

; #define LAS __attribute__((address_space(3)))
; __global__ void __launch_bounds__(512, 2) mk_fwd(Args a) {
;     ...
;     for (int rep0 = 0; rep0 < REP_P0; ++rep0) {
;         LAS float* scr = (LAS float*)(lds + wave * 16384);
;         constexpr int I_IN = (DM / 64) * (NIN / 32), I_A = (512 / 64) * (DM / 32), I_B = (256 / 64) * (DM / 32), I_O = (DM / 64) * (DM / 32), I_U = (DM / 64) * (DFF / 32), I_D = (DFF / 64) * (DM / 32);
;         constexpr int NIT = I_IN + I_A + I_B + I_O + I_U + I_D;
;         for (int it = gw; it < NIT; it += NGW) {
;             int r = it;
;             if (r < I_IN) { p0_transpose_item_fp8(w_in, DM, NIN, (unsigned char*)Win_t, scr, r, lane, 32.f); continue; } r -= I_IN;
;             if (r < I_A) { p0_transpose_item_fp8(w_a, 512, DM, (unsigned char*)Wa_t, scr, r, lane, 16.f, 768, 0); continue; }     r -= I_A;
;             if (r < I_B) { p0_transpose_item_fp8(w_b, 256, DM, (unsigned char*)Wa_t, scr, r, lane, 16.f, 768, 512); continue; }     r -= I_B;
;             if (r < I_O) { p0_transpose_item_fp8(w_out, DM, DM, (unsigned char*)Wout_t, scr, r, lane, 32.f); continue; } r -= I_O;
;             if (r < I_U) { p0_transpose_item(w_up, DM, DFF, Wup_t, g_mlp, scr, r, lane); continue; } r -= I_U;
;             p0_transpose_item(w_dn, DFF, DM, Wdn_t, nullptr, scr, r, lane);
;         }
;         f32x4 gv[4];
; #pragma unroll
;         for (int j = 0; j < 4; ++j) gv[j] = ((const f32x4*)g_mix)[lane + 64 * j];
;         for (int m = gw; m < TT; m += 2 * NGW) {
.Lmy_p0_fix:
	s_add_u32 s16, s22, 0x3000000
	s_addc_u32 s17, s23, 0
	s_mov_b64 s[12:13], -1
.LBB0_65:
	s_cmp_lg_u32 s66, 1
	s_cbranch_scc1 .Lmy_p0_end
	s_mov_b32 s66, 2
	s_mov_b32 s0, s67
	s_mov_b32 s6, s68
	s_mov_b64 s[8:9], s[70:71]
	s_mov_b64 s[12:13], s[72:73]
	s_mov_b64 s[14:15], s[74:75]
	s_mov_b64 s[16:17], s[78:79]
	s_mov_b64 s[42:43], s[80:81]
	s_branch .Lmy_p0_T
